# v63 + fused-LN row-stat exchange: acquire fence after the counter poll dropped (payload is sc1 write-through, read back with sc1 loads)
# baseline (speedup 1.0000x reference)
;     __device__ __forceinline__ void fused(f32x4 (&acc)[2][2][4][2], const Unit& u, int wr, int wc, int fr, int fq, LAS unsigned char* lds, int wid, int lane) const {
;     ...
;         if (wid == 0) {
;             bool dead = false; const unsigned long long t0 = __builtin_amdgcn_s_memrealtime();
;             for (;;) {
;                 if ((unsigned)__builtin_amdgcn_readfirstlane(__hip_atomic_load(cw, __ATOMIC_RELAXED, __HIP_MEMORY_SCOPE_AGENT)) >= 64u) break;
;                 if (__builtin_amdgcn_s_memrealtime() - t0 > 2000000ull) { if (lane == 0) __hip_atomic_store(tmo, 1u, __ATOMIC_RELAXED, __HIP_MEMORY_SCOPE_AGENT); dead = true; break; }
;                 __builtin_amdgcn_s_sleep(2);
;             }
;             __builtin_amdgcn_fence(__ATOMIC_ACQUIRE, "agent");
;             if (lane == 0) flag[0] = dead ? 1u : 0u;
;         }
;         asm volatile("s_waitcnt vmcnt(0) lgkmcnt(0)" ::: "memory"); __builtin_amdgcn_s_barrier(); asm volatile("" ::: "memory");
;         const bool bad = flag[0] != 0u;
.LBB0_1356:
	s_waitcnt vmcnt(0)
	s_and_b64 exec, exec, s[42:43]
	v_cndmask_b32_e64 v26, 0, 1, s[18:19]
	ds_write_b32 v203, v26 offset:10240

;     __device__ __forceinline__ void fused(f32x4 (&acc)[2][2][4][2], const Unit& u, int wr, int wc, int fr, int fq, LAS unsigned char* lds, int wid, int lane) const {
;     ...
;         if (wid == 0) {
;             bool dead = false; const unsigned long long t0 = __builtin_amdgcn_s_memrealtime();
;             for (;;) {
;                 if ((unsigned)__builtin_amdgcn_readfirstlane(__hip_atomic_load(cw, __ATOMIC_RELAXED, __HIP_MEMORY_SCOPE_AGENT)) >= 64u) break;
;                 if (__builtin_amdgcn_s_memrealtime() - t0 > 2000000ull) { if (lane == 0) __hip_atomic_store(tmo, 1u, __ATOMIC_RELAXED, __HIP_MEMORY_SCOPE_AGENT); dead = true; break; }
;                 __builtin_amdgcn_s_sleep(2);
;             }
;             __builtin_amdgcn_fence(__ATOMIC_ACQUIRE, "agent");
;             if (lane == 0) flag[0] = dead ? 1u : 0u;
;         }
;         asm volatile("s_waitcnt vmcnt(0) lgkmcnt(0)" ::: "memory"); __builtin_amdgcn_s_barrier(); asm volatile("" ::: "memory");
;         const bool bad = flag[0] != 0u;
.LBB0_1785:
	s_waitcnt vmcnt(0)
	s_and_b64 exec, exec, s[42:43]
	v_cndmask_b32_e64 v26, 0, 1, s[24:25]
	ds_write_b32 v203, v26 offset:10240
